# K-loop edge (all 3 copies): loop-carried counter/pointer updates moved before the loop-back barrier; head pointer-select SALU chain moved behind segment-1 ds_reads
# baseline (speedup 1.0000x reference)
; #define PG8_STAGE(bufoff, gbase, voff) do { _Pragma("unroll") for (int _i = 0; _i < 2; ++_i) \
;         __builtin_amdgcn_global_load_lds((const unsigned*)((const char*)(gbase) + (voff)[_i]), (PG8_LAS unsigned*)(lds + (bufoff) + ldsw + _i * 8192), 16, 0, 0); } while (0)
; #define PG8_LDA(dst, b, h) do { _Pragma("unroll") for (int m = 0; m < 4; ++m) _Pragma("unroll") for (int k = 0; k < 2; ++k) dst[m][k] = *(const PG8_LAS bf16x8*)(lds + PG8_SA(b, h) + aoff + m * 2048 + k * 1024); } while (0)
; #define PG8_LDB(dst, b, h) do { _Pragma("unroll") for (int n = 0; n < 2; ++n) _Pragma("unroll") for (int k = 0; k < 2; ++k) dst[n][k] = *(const PG8_LAS bf16x8*)(lds + PG8_SB(b, h) + boff + n * 2048 + k * 1024); } while (0)
; #define PG8_MMA(ai, bj, At, Bt) do { __builtin_amdgcn_s_setprio(1); _Pragma("unroll") for (int m = 0; m < 4; ++m) _Pragma("unroll") for (int n = 0; n < 2; ++n) _Pragma("unroll") for (int k = 0; k < 2; ++k) \
;         acc[ai][bj][m][n] = __builtin_amdgcn_mfma_f32_16x16x32_bf16(Bt[n][k], At[m][k], acc[ai][bj][m][n], 0, 0, 0); __builtin_amdgcn_s_setprio(0); } while (0)
; #define PG8_WAIT_V(n) asm volatile("s_waitcnt vmcnt(" #n ")" ::: "memory")
; #define PG8_WAIT_L(n) asm volatile("s_waitcnt lgkmcnt(" #n ")" ::: "memory")
; #define PG8_BAR __builtin_amdgcn_s_barrier()
; #define PG8_SCHED __builtin_amdgcn_sched_barrier(0)
; template <class Epi, class Sched, bool ALIGN_EPI = false, bool SP2 = false>
; __device__ __forceinline__ void gemm_phase(PG8_LAS unsigned char* lds, const Gemm g, const Sched& S, const Epi& E, const int wave_s) {
;     ...
;             PG8_LDB(B0, 0, 0); PG8_LDB(B1, 0, 1); PG8_SCHED; PG8_LDA(At, 0, 0); PG8_STAGE(PG8_SA(1, 1), a1 + hstep, voffA);
;             PG8_WAIT_V(8); PG8_WAIT_L(0); PG8_BAR; PG8_MMA(0, 0, At, B0); PG8_MMA(0, 1, At, B1); PG8_BAR; PG8_SCHED;
;             PG8_LDA(At, 0, 1); PG8_STAGE(PG8_SB(0, 0), b2, voffB); PG8_STAGE(PG8_SB(0, 1), b2 + hstep, voffB); PG8_STAGE(PG8_SA(0, 0), a2, voffA);
;             PG8_WAIT_V(8); PG8_WAIT_L(0); PG8_BAR; PG8_MMA(1, 0, At, B0); PG8_MMA(1, 1, At, B1); PG8_BAR; PG8_SCHED;
.LBB0_301:
	s_add_i32 s55, 0, 0x10000
	s_add_i32 s58, 0, 0x14000
	v_add_u32_e32 v156, s55, v146
	v_add_u32_e32 v160, s58, v146
	ds_read_b128 v[140:143], v156
	ds_read_b128 v[148:151], v156 offset:1024
	ds_read_b128 v[152:155], v156 offset:2048
	ds_read_b128 v[156:159], v156 offset:3072
	ds_read_b128 v[174:177], v160
	ds_read_b128 v[178:181], v160 offset:1024
	ds_read_b128 v[182:185], v160 offset:2048
	ds_read_b128 v[186:189], v160 offset:3072
	v_lshl_add_u64 v[160:161], s[34:35], 0, v[136:137]
	s_add_i32 m0, s43, 0xc000
	ds_read_b128 v[190:193], v147
	ds_read_b128 v[210:213], v147 offset:1024
	ds_read_b128 v[214:217], v147 offset:2048
	ds_read_b128 v[218:221], v147 offset:3072
	ds_read_b128 v[222:225], v147 offset:4096
	ds_read_b128 v[226:229], v147 offset:5120
	ds_read_b128 v[230:233], v147 offset:6144
	ds_read_b128 v[234:237], v147 offset:7168
	s_add_u32 s2, s34, 0xfffc0080
	s_addc_u32 s3, s35, -1
	s_cmp_eq_u32 s54, 12
	s_cselect_b32 s37, s9, s3
	s_cselect_b32 s36, s25, s2
	s_cselect_b32 s3, s23, s53
	s_cselect_b32 s2, s31, s52
	global_load_lds_dwordx4 v[160:161], off
	v_lshl_add_u64 v[160:161], s[34:35], 0, v[138:139]
	s_add_i32 m0, s43, 0xe000
	s_nop 0
	global_load_lds_dwordx4 v[160:161], off
	s_waitcnt vmcnt(8)
	s_waitcnt lgkmcnt(0)
	s_barrier
	s_setprio 1
	s_waitcnt lgkmcnt(0)
	v_mfma_f32_16x16x32_bf16 v[124:127], v[140:143], v[190:193], v[124:127]
	v_mfma_f32_16x16x32_bf16 v[120:123], v[152:155], v[190:193], v[120:123]
	v_mfma_f32_16x16x32_bf16 v[108:111], v[140:143], v[214:217], v[108:111]
	v_mfma_f32_16x16x32_bf16 v[104:107], v[152:155], v[214:217], v[104:107]
	v_mfma_f32_16x16x32_bf16 v[92:95], v[140:143], v[222:225], v[92:95]
	v_mfma_f32_16x16x32_bf16 v[88:91], v[152:155], v[222:225], v[88:91]
	v_mfma_f32_16x16x32_bf16 v[76:79], v[140:143], v[230:233], v[76:79]
	v_mfma_f32_16x16x32_bf16 v[72:75], v[152:155], v[230:233], v[72:75]
	v_mfma_f32_16x16x32_bf16 v[124:127], v[148:151], v[210:213], v[124:127]
	v_mfma_f32_16x16x32_bf16 v[120:123], v[156:159], v[210:213], v[120:123]
	v_mfma_f32_16x16x32_bf16 v[108:111], v[148:151], v[218:221], v[108:111]
	v_mfma_f32_16x16x32_bf16 v[104:107], v[156:159], v[218:221], v[104:107]
	v_mfma_f32_16x16x32_bf16 v[92:95], v[148:151], v[226:229], v[92:95]
	v_mfma_f32_16x16x32_bf16 v[88:91], v[156:159], v[226:229], v[88:91]
	v_mfma_f32_16x16x32_bf16 v[76:79], v[148:151], v[234:237], v[76:79]
	v_mfma_f32_16x16x32_bf16 v[72:75], v[156:159], v[234:237], v[72:75]
	s_setprio 0
	s_setprio 1
	v_mfma_f32_16x16x32_bf16 v[116:119], v[174:177], v[190:193], v[116:119]
	v_mfma_f32_16x16x32_bf16 v[112:115], v[182:185], v[190:193], v[112:115]
	v_mfma_f32_16x16x32_bf16 v[100:103], v[174:177], v[214:217], v[100:103]
	v_mfma_f32_16x16x32_bf16 v[96:99], v[182:185], v[214:217], v[96:99]
	v_mfma_f32_16x16x32_bf16 v[84:87], v[174:177], v[222:225], v[84:87]
	v_mfma_f32_16x16x32_bf16 v[80:83], v[182:185], v[222:225], v[80:83]
	v_mfma_f32_16x16x32_bf16 v[68:71], v[174:177], v[230:233], v[68:71]
	v_mfma_f32_16x16x32_bf16 v[64:67], v[182:185], v[230:233], v[64:67]
	v_mfma_f32_16x16x32_bf16 v[116:119], v[178:181], v[210:213], v[116:119]
	v_mfma_f32_16x16x32_bf16 v[112:115], v[186:189], v[210:213], v[112:115]
	v_mfma_f32_16x16x32_bf16 v[100:103], v[178:181], v[218:221], v[100:103]
	v_mfma_f32_16x16x32_bf16 v[96:99], v[186:189], v[218:221], v[96:99]
	v_mfma_f32_16x16x32_bf16 v[84:87], v[178:181], v[226:229], v[84:87]
	v_mfma_f32_16x16x32_bf16 v[80:83], v[186:189], v[226:229], v[80:83]
	v_mfma_f32_16x16x32_bf16 v[68:71], v[178:181], v[234:237], v[68:71]
	v_mfma_f32_16x16x32_bf16 v[64:67], v[186:189], v[234:237], v[64:67]
	s_setprio 0
	s_barrier
	s_add_i32 s55, s55, s42
	v_lshl_add_u64 v[160:161], s[2:3], 0, v[128:129]
	s_mov_b32 m0, s55
	ds_read_b128 v[190:193], v147 offset:16384
	ds_read_b128 v[210:213], v147 offset:17408
	ds_read_b128 v[214:217], v147 offset:18432
	ds_read_b128 v[218:221], v147 offset:19456
	ds_read_b128 v[222:225], v147 offset:20480
	ds_read_b128 v[226:229], v147 offset:21504
	ds_read_b128 v[230:233], v147 offset:22528
	ds_read_b128 v[234:237], v147 offset:23552
	global_load_lds_dwordx4 v[160:161], off
	s_add_i32 m0, s55, 0x2000
	s_add_u32 s56, s2, 0x40000
	v_lshl_add_u64 v[194:195], s[2:3], 0, v[134:135]
	s_addc_u32 s57, s3, 0
	s_add_i32 s55, s58, s42
	global_load_lds_dwordx4 v[194:195], off
	v_lshl_add_u64 v[206:207], s[56:57], 0, v[128:129]
	s_mov_b32 m0, s55
	v_lshl_add_u64 v[238:239], s[36:37], 0, v[132:133]
	global_load_lds_dwordx4 v[206:207], off
	v_lshl_add_u64 v[206:207], s[56:57], 0, v[134:135]
	s_add_i32 m0, s55, 0x2000
	s_nop 0
	global_load_lds_dwordx4 v[206:207], off
	v_lshl_add_u64 v[206:207], s[36:37], 0, v[130:131]
	s_mov_b32 m0, s43
	s_nop 0
	global_load_lds_dwordx4 v[206:207], off
	s_mov_b32 m0, s44
	s_nop 0
	global_load_lds_dwordx4 v[238:239], off
	s_waitcnt vmcnt(8)
	s_waitcnt lgkmcnt(0)
	s_barrier
; #define PG8_STAGE(bufoff, gbase, voff) do { _Pragma("unroll") for (int _i = 0; _i < 2; ++_i) \
;         __builtin_amdgcn_global_load_lds((const unsigned*)((const char*)(gbase) + (voff)[_i]), (PG8_LAS unsigned*)(lds + (bufoff) + ldsw + _i * 8192), 16, 0, 0); } while (0)
; #define PG8_LDA(dst, b, h) do { _Pragma("unroll") for (int m = 0; m < 4; ++m) _Pragma("unroll") for (int k = 0; k < 2; ++k) dst[m][k] = *(const PG8_LAS bf16x8*)(lds + PG8_SA(b, h) + aoff + m * 2048 + k * 1024); } while (0)
; #define PG8_LDB(dst, b, h) do { _Pragma("unroll") for (int n = 0; n < 2; ++n) _Pragma("unroll") for (int k = 0; k < 2; ++k) dst[n][k] = *(const PG8_LAS bf16x8*)(lds + PG8_SB(b, h) + boff + n * 2048 + k * 1024); } while (0)
; #define PG8_MMA(ai, bj, At, Bt) do { __builtin_amdgcn_s_setprio(1); _Pragma("unroll") for (int m = 0; m < 4; ++m) _Pragma("unroll") for (int n = 0; n < 2; ++n) _Pragma("unroll") for (int k = 0; k < 2; ++k) \
;         acc[ai][bj][m][n] = __builtin_amdgcn_mfma_f32_16x16x32_bf16(Bt[n][k], At[m][k], acc[ai][bj][m][n], 0, 0, 0); __builtin_amdgcn_s_setprio(0); } while (0)
; #define PG8_WAIT_V(n) asm volatile("s_waitcnt vmcnt(" #n ")" ::: "memory")
; #define PG8_WAIT_L(n) asm volatile("s_waitcnt lgkmcnt(" #n ")" ::: "memory")
; #define PG8_BAR __builtin_amdgcn_s_barrier()
; #define PG8_SCHED __builtin_amdgcn_sched_barrier(0)
; template <class Epi, class Sched, bool ALIGN_EPI = false, bool SP2 = false>
; __device__ __forceinline__ void gemm_phase(PG8_LAS unsigned char* lds, const Gemm g, const Sched& S, const Epi& E, const int wave_s) {
;     ...
;             PG8_WAIT_V(8); PG8_WAIT_L(0); PG8_BAR; PG8_MMA(1, 0, At, B0); PG8_MMA(1, 1, At, B1); PG8_BAR; PG8_SCHED;
;             PG8_LDB(B0, 1, 0); PG8_LDB(B1, 1, 1); PG8_SCHED; PG8_LDA(At, 1, 0); PG8_STAGE(PG8_SA(0, 1), a2 + hstep, voffA);
;             PG8_WAIT_V(8); PG8_WAIT_L(0); PG8_BAR; PG8_MMA(0, 0, At, B0); PG8_MMA(0, 1, At, B1); PG8_BAR; PG8_SCHED;
	s_setprio 1
	s_waitcnt lgkmcnt(0)
	v_mfma_f32_16x16x32_bf16 v[60:63], v[140:143], v[190:193], v[60:63]
	v_mfma_f32_16x16x32_bf16 v[56:59], v[152:155], v[190:193], v[56:59]
	v_mfma_f32_16x16x32_bf16 v[44:47], v[140:143], v[214:217], v[44:47]
	v_mfma_f32_16x16x32_bf16 v[40:43], v[152:155], v[214:217], v[40:43]
	v_mfma_f32_16x16x32_bf16 v[28:31], v[140:143], v[222:225], v[28:31]
	v_mfma_f32_16x16x32_bf16 v[24:27], v[152:155], v[222:225], v[24:27]
	v_mfma_f32_16x16x32_bf16 v[12:15], v[140:143], v[230:233], v[12:15]
	v_mfma_f32_16x16x32_bf16 v[8:11], v[152:155], v[230:233], v[8:11]
	v_mfma_f32_16x16x32_bf16 v[60:63], v[148:151], v[210:213], v[60:63]
	v_mfma_f32_16x16x32_bf16 v[56:59], v[156:159], v[210:213], v[56:59]
	v_mfma_f32_16x16x32_bf16 v[44:47], v[148:151], v[218:221], v[44:47]
	v_mfma_f32_16x16x32_bf16 v[40:43], v[156:159], v[218:221], v[40:43]
	v_mfma_f32_16x16x32_bf16 v[28:31], v[148:151], v[226:229], v[28:31]
	v_mfma_f32_16x16x32_bf16 v[24:27], v[156:159], v[226:229], v[24:27]
	v_mfma_f32_16x16x32_bf16 v[12:15], v[148:151], v[234:237], v[12:15]
	v_mfma_f32_16x16x32_bf16 v[8:11], v[156:159], v[234:237], v[8:11]
	s_setprio 0
	s_setprio 1
	v_mfma_f32_16x16x32_bf16 v[52:55], v[174:177], v[190:193], v[52:55]
	v_mfma_f32_16x16x32_bf16 v[48:51], v[182:185], v[190:193], v[48:51]
	v_mfma_f32_16x16x32_bf16 v[36:39], v[174:177], v[214:217], v[36:39]
	v_mfma_f32_16x16x32_bf16 v[32:35], v[182:185], v[214:217], v[32:35]
	v_mfma_f32_16x16x32_bf16 v[20:23], v[174:177], v[222:225], v[20:23]
	v_mfma_f32_16x16x32_bf16 v[16:19], v[182:185], v[222:225], v[16:19]
	v_mfma_f32_16x16x32_bf16 v[4:7], v[174:177], v[230:233], v[4:7]
	v_mfma_f32_16x16x32_bf16 v[0:3], v[182:185], v[230:233], v[0:3]
	v_mfma_f32_16x16x32_bf16 v[52:55], v[178:181], v[210:213], v[52:55]
	v_mfma_f32_16x16x32_bf16 v[48:51], v[186:189], v[210:213], v[48:51]
	v_mfma_f32_16x16x32_bf16 v[36:39], v[178:181], v[218:221], v[36:39]
	v_mfma_f32_16x16x32_bf16 v[32:35], v[186:189], v[218:221], v[32:35]
	v_mfma_f32_16x16x32_bf16 v[20:23], v[178:181], v[226:229], v[20:23]
	v_mfma_f32_16x16x32_bf16 v[16:19], v[186:189], v[226:229], v[16:19]
	v_mfma_f32_16x16x32_bf16 v[4:7], v[178:181], v[234:237], v[4:7]
	v_mfma_f32_16x16x32_bf16 v[0:3], v[186:189], v[234:237], v[0:3]
	s_setprio 0
	s_barrier
	s_add_i32 s55, 0, 0x18000
	s_add_i32 s56, 0, 0x1c000
	v_add_u32_e32 v156, s55, v146
	v_add_u32_e32 v171, s56, v146
	ds_read_b128 v[140:143], v156
	ds_read_b128 v[148:151], v156 offset:1024
	ds_read_b128 v[152:155], v156 offset:2048
	ds_read_b128 v[156:159], v156 offset:3072
	ds_read_b128 v[174:177], v171
	ds_read_b128 v[178:181], v171 offset:1024
	ds_read_b128 v[182:185], v171 offset:2048
	ds_read_b128 v[186:189], v171 offset:3072
	s_add_u32 s36, s36, 0x40000
	s_addc_u32 s37, s37, 0
	s_mov_b32 m0, s45
	v_lshl_add_u64 v[240:241], s[36:37], 0, v[130:131]
	ds_read_b128 v[190:193], v147 offset:32768
	ds_read_b128 v[210:213], v147 offset:33792
	ds_read_b128 v[214:217], v147 offset:34816
	ds_read_b128 v[218:221], v147 offset:35840
	ds_read_b128 v[222:225], v147 offset:36864
	ds_read_b128 v[226:229], v147 offset:37888
	ds_read_b128 v[230:233], v147 offset:38912
	ds_read_b128 v[234:237], v147 offset:39936
	global_load_lds_dwordx4 v[240:241], off
	v_lshl_add_u64 v[240:241], s[36:37], 0, v[132:133]
	s_mov_b32 m0, s46
	s_nop 0
	global_load_lds_dwordx4 v[240:241], off
	s_waitcnt vmcnt(8)
	s_waitcnt lgkmcnt(0)
	s_barrier
	s_setprio 1
	s_waitcnt lgkmcnt(0)
	v_mfma_f32_16x16x32_bf16 v[124:127], v[140:143], v[190:193], v[124:127]
	v_mfma_f32_16x16x32_bf16 v[120:123], v[152:155], v[190:193], v[120:123]
	v_mfma_f32_16x16x32_bf16 v[108:111], v[140:143], v[214:217], v[108:111]
	v_mfma_f32_16x16x32_bf16 v[104:107], v[152:155], v[214:217], v[104:107]
	v_mfma_f32_16x16x32_bf16 v[92:95], v[140:143], v[222:225], v[92:95]
	v_mfma_f32_16x16x32_bf16 v[88:91], v[152:155], v[222:225], v[88:91]
	v_mfma_f32_16x16x32_bf16 v[76:79], v[140:143], v[230:233], v[76:79]
	v_mfma_f32_16x16x32_bf16 v[72:75], v[152:155], v[230:233], v[72:75]
	v_mfma_f32_16x16x32_bf16 v[124:127], v[148:151], v[210:213], v[124:127]
	v_mfma_f32_16x16x32_bf16 v[120:123], v[156:159], v[210:213], v[120:123]
	v_mfma_f32_16x16x32_bf16 v[108:111], v[148:151], v[218:221], v[108:111]
	v_mfma_f32_16x16x32_bf16 v[104:107], v[156:159], v[218:221], v[104:107]
	v_mfma_f32_16x16x32_bf16 v[92:95], v[148:151], v[226:229], v[92:95]
	v_mfma_f32_16x16x32_bf16 v[88:91], v[156:159], v[226:229], v[88:91]
	v_mfma_f32_16x16x32_bf16 v[76:79], v[148:151], v[234:237], v[76:79]
	v_mfma_f32_16x16x32_bf16 v[72:75], v[156:159], v[234:237], v[72:75]
	s_setprio 0
	s_setprio 1
	v_mfma_f32_16x16x32_bf16 v[116:119], v[174:177], v[190:193], v[116:119]
	v_mfma_f32_16x16x32_bf16 v[112:115], v[182:185], v[190:193], v[112:115]
	v_mfma_f32_16x16x32_bf16 v[100:103], v[174:177], v[214:217], v[100:103]
	v_mfma_f32_16x16x32_bf16 v[96:99], v[182:185], v[214:217], v[96:99]
	v_mfma_f32_16x16x32_bf16 v[84:87], v[174:177], v[222:225], v[84:87]
	v_mfma_f32_16x16x32_bf16 v[80:83], v[182:185], v[222:225], v[80:83]
	v_mfma_f32_16x16x32_bf16 v[68:71], v[174:177], v[230:233], v[68:71]
	v_mfma_f32_16x16x32_bf16 v[64:67], v[182:185], v[230:233], v[64:67]
	v_mfma_f32_16x16x32_bf16 v[116:119], v[178:181], v[210:213], v[116:119]
	v_mfma_f32_16x16x32_bf16 v[112:115], v[186:189], v[210:213], v[112:115]
	v_mfma_f32_16x16x32_bf16 v[100:103], v[178:181], v[218:221], v[100:103]
	v_mfma_f32_16x16x32_bf16 v[96:99], v[186:189], v[218:221], v[96:99]
	v_mfma_f32_16x16x32_bf16 v[84:87], v[178:181], v[226:229], v[84:87]
	v_mfma_f32_16x16x32_bf16 v[80:83], v[186:189], v[226:229], v[80:83]
	v_mfma_f32_16x16x32_bf16 v[68:71], v[178:181], v[234:237], v[68:71]
	v_mfma_f32_16x16x32_bf16 v[64:67], v[186:189], v[234:237], v[64:67]
	s_setprio 0
	s_barrier
; #define PG8_STAGE(bufoff, gbase, voff) do { _Pragma("unroll") for (int _i = 0; _i < 2; ++_i) \
;         __builtin_amdgcn_global_load_lds((const unsigned*)((const char*)(gbase) + (voff)[_i]), (PG8_LAS unsigned*)(lds + (bufoff) + ldsw + _i * 8192), 16, 0, 0); } while (0)
; #define PG8_LDA(dst, b, h) do { _Pragma("unroll") for (int m = 0; m < 4; ++m) _Pragma("unroll") for (int k = 0; k < 2; ++k) dst[m][k] = *(const PG8_LAS bf16x8*)(lds + PG8_SA(b, h) + aoff + m * 2048 + k * 1024); } while (0)
; #define PG8_MMA(ai, bj, At, Bt) do { __builtin_amdgcn_s_setprio(1); _Pragma("unroll") for (int m = 0; m < 4; ++m) _Pragma("unroll") for (int n = 0; n < 2; ++n) _Pragma("unroll") for (int k = 0; k < 2; ++k) \
;         acc[ai][bj][m][n] = __builtin_amdgcn_mfma_f32_16x16x32_bf16(Bt[n][k], At[m][k], acc[ai][bj][m][n], 0, 0, 0); __builtin_amdgcn_s_setprio(0); } while (0)
; #define PG8_WAIT_V(n) asm volatile("s_waitcnt vmcnt(" #n ")" ::: "memory")
; #define PG8_WAIT_L(n) asm volatile("s_waitcnt lgkmcnt(" #n ")" ::: "memory")
; #define PG8_BAR __builtin_amdgcn_s_barrier()
; #define PG8_SCHED __builtin_amdgcn_sched_barrier(0)
; template <class Epi, class Sched, bool ALIGN_EPI = false, bool SP2 = false>
; __device__ __forceinline__ void gemm_phase(PG8_LAS unsigned char* lds, const Gemm g, const Sched& S, const Epi& E, const int wave_s) {
;     ...
;         for (int t = 0; t < clen; t += 2) {
;     ...
;             PG8_WAIT_V(8); PG8_WAIT_L(0); PG8_BAR; PG8_MMA(0, 0, At, B0); PG8_MMA(0, 1, At, B1); PG8_BAR; PG8_SCHED;
;             PG8_LDA(At, 1, 1); PG8_STAGE(PG8_SB(1, 0), b3, voffB); PG8_STAGE(PG8_SB(1, 1), b3 + hstep, voffB); PG8_STAGE(PG8_SA(1, 0), a3, voffA);
;             PG8_WAIT_V(8); PG8_WAIT_L(0); PG8_BAR; PG8_MMA(1, 0, At, B0); PG8_MMA(1, 1, At, B1); PG8_BAR; PG8_SCHED;
	s_add_i32 s36, s55, s42
	v_lshl_add_u64 v[160:161], v[160:161], 0, s[4:5]
	s_mov_b32 m0, s36
	ds_read_b128 v[190:193], v147 offset:49152
	ds_read_b128 v[210:213], v147 offset:50176
	ds_read_b128 v[214:217], v147 offset:51200
	ds_read_b128 v[218:221], v147 offset:52224
	ds_read_b128 v[222:225], v147 offset:53248
	ds_read_b128 v[226:229], v147 offset:54272
	ds_read_b128 v[230:233], v147 offset:55296
	ds_read_b128 v[234:237], v147 offset:56320
	global_load_lds_dwordx4 v[160:161], off
	s_add_i32 m0, s36, 0x2000
	s_add_u32 s2, s2, 0x40080
	v_lshl_add_u64 v[160:161], v[194:195], 0, s[4:5]
	s_addc_u32 s3, s3, 0
	s_add_i32 s36, s56, s42
	global_load_lds_dwordx4 v[160:161], off
	v_lshl_add_u64 v[160:161], s[2:3], 0, v[128:129]
	s_mov_b32 m0, s36
	s_nop 0
	global_load_lds_dwordx4 v[160:161], off
	v_lshl_add_u64 v[160:161], s[2:3], 0, v[134:135]
	s_add_i32 m0, s36, 0x2000
	s_nop 0
	global_load_lds_dwordx4 v[160:161], off
	v_lshl_add_u64 v[160:161], v[206:207], 0, s[4:5]
	s_mov_b32 m0, s49
	s_nop 0
	global_load_lds_dwordx4 v[160:161], off
	v_lshl_add_u64 v[160:161], v[238:239], 0, s[4:5]
	s_mov_b32 m0, s50
	s_nop 0
	global_load_lds_dwordx4 v[160:161], off
	s_waitcnt vmcnt(8)
	s_waitcnt lgkmcnt(0)
	s_barrier
	s_setprio 1
	s_waitcnt lgkmcnt(0)
	v_mfma_f32_16x16x32_bf16 v[60:63], v[140:143], v[190:193], v[60:63]
	v_mfma_f32_16x16x32_bf16 v[56:59], v[152:155], v[190:193], v[56:59]
	v_mfma_f32_16x16x32_bf16 v[44:47], v[140:143], v[214:217], v[44:47]
	v_mfma_f32_16x16x32_bf16 v[40:43], v[152:155], v[214:217], v[40:43]
	v_mfma_f32_16x16x32_bf16 v[28:31], v[140:143], v[222:225], v[28:31]
	v_mfma_f32_16x16x32_bf16 v[24:27], v[152:155], v[222:225], v[24:27]
	v_mfma_f32_16x16x32_bf16 v[12:15], v[140:143], v[230:233], v[12:15]
	v_mfma_f32_16x16x32_bf16 v[8:11], v[152:155], v[230:233], v[8:11]
	v_mfma_f32_16x16x32_bf16 v[60:63], v[148:151], v[210:213], v[60:63]
	v_mfma_f32_16x16x32_bf16 v[56:59], v[156:159], v[210:213], v[56:59]
	v_mfma_f32_16x16x32_bf16 v[44:47], v[148:151], v[218:221], v[44:47]
	v_mfma_f32_16x16x32_bf16 v[40:43], v[156:159], v[218:221], v[40:43]
	v_mfma_f32_16x16x32_bf16 v[28:31], v[148:151], v[226:229], v[28:31]
	v_mfma_f32_16x16x32_bf16 v[24:27], v[156:159], v[226:229], v[24:27]
	v_mfma_f32_16x16x32_bf16 v[12:15], v[148:151], v[234:237], v[12:15]
	v_mfma_f32_16x16x32_bf16 v[8:11], v[156:159], v[234:237], v[8:11]
	s_setprio 0
	s_setprio 1
	v_mfma_f32_16x16x32_bf16 v[52:55], v[174:177], v[190:193], v[52:55]
	v_mfma_f32_16x16x32_bf16 v[48:51], v[182:185], v[190:193], v[48:51]
	v_mfma_f32_16x16x32_bf16 v[36:39], v[174:177], v[214:217], v[36:39]
	v_mfma_f32_16x16x32_bf16 v[32:35], v[182:185], v[214:217], v[32:35]
	v_mfma_f32_16x16x32_bf16 v[20:23], v[174:177], v[222:225], v[20:23]
	v_mfma_f32_16x16x32_bf16 v[16:19], v[182:185], v[222:225], v[16:19]
	v_mfma_f32_16x16x32_bf16 v[4:7], v[174:177], v[230:233], v[4:7]
	v_mfma_f32_16x16x32_bf16 v[0:3], v[182:185], v[230:233], v[0:3]
	v_mfma_f32_16x16x32_bf16 v[52:55], v[178:181], v[210:213], v[52:55]
	v_mfma_f32_16x16x32_bf16 v[48:51], v[186:189], v[210:213], v[48:51]
	v_mfma_f32_16x16x32_bf16 v[36:39], v[178:181], v[218:221], v[36:39]
	v_mfma_f32_16x16x32_bf16 v[32:35], v[186:189], v[218:221], v[32:35]
	v_mfma_f32_16x16x32_bf16 v[20:23], v[178:181], v[226:229], v[20:23]
	v_mfma_f32_16x16x32_bf16 v[16:19], v[186:189], v[226:229], v[16:19]
	v_mfma_f32_16x16x32_bf16 v[4:7], v[178:181], v[234:237], v[4:7]
	v_mfma_f32_16x16x32_bf16 v[0:3], v[186:189], v[234:237], v[0:3]
	s_setprio 0
	s_add_i32 s54, s54, 2
	s_add_u32 s34, s34, 0x100
	s_addc_u32 s35, s35, 0
	s_add_u32 s52, s52, 0x100
	s_addc_u32 s53, s53, 0
	s_cmp_gt_u32 s54, 13
	s_barrier
	s_cbranch_scc0 .LBB0_301
	s_and_b64 vcc, exec, s[20:21]
	s_cbranch_vccz .LBB0_304
	s_barrier

; #define PG8_STAGE(bufoff, gbase, voff) do { _Pragma("unroll") for (int _i = 0; _i < 2; ++_i) \
;         __builtin_amdgcn_global_load_lds((const unsigned*)((const char*)(gbase) + (voff)[_i]), (PG8_LAS unsigned*)(lds + (bufoff) + ldsw + _i * 8192), 16, 0, 0); } while (0)
; #define PG8_LDA(dst, b, h) do { _Pragma("unroll") for (int m = 0; m < 4; ++m) _Pragma("unroll") for (int k = 0; k < 2; ++k) dst[m][k] = *(const PG8_LAS bf16x8*)(lds + PG8_SA(b, h) + aoff + m * 2048 + k * 1024); } while (0)
; #define PG8_LDB(dst, b, h) do { _Pragma("unroll") for (int n = 0; n < 2; ++n) _Pragma("unroll") for (int k = 0; k < 2; ++k) dst[n][k] = *(const PG8_LAS bf16x8*)(lds + PG8_SB(b, h) + boff + n * 2048 + k * 1024); } while (0)
; #define PG8_MMA(ai, bj, At, Bt) do { __builtin_amdgcn_s_setprio(1); _Pragma("unroll") for (int m = 0; m < 4; ++m) _Pragma("unroll") for (int n = 0; n < 2; ++n) _Pragma("unroll") for (int k = 0; k < 2; ++k) \
;         acc[ai][bj][m][n] = __builtin_amdgcn_mfma_f32_16x16x32_bf16(Bt[n][k], At[m][k], acc[ai][bj][m][n], 0, 0, 0); __builtin_amdgcn_s_setprio(0); } while (0)
; #define PG8_WAIT_V(n) asm volatile("s_waitcnt vmcnt(" #n ")" ::: "memory")
; #define PG8_WAIT_L(n) asm volatile("s_waitcnt lgkmcnt(" #n ")" ::: "memory")
; #define PG8_BAR __builtin_amdgcn_s_barrier()
; #define PG8_SCHED __builtin_amdgcn_sched_barrier(0)
; template <class Epi, class Sched, bool ALIGN_EPI = false, bool SP2 = false>
; __device__ __forceinline__ void gemm_phase(PG8_LAS unsigned char* lds, const Gemm g, const Sched& S, const Epi& E, const int wave_s) {
;     ...
;             PG8_LDB(B0, 0, 0); PG8_LDB(B1, 0, 1); PG8_SCHED; PG8_LDA(At, 0, 0); PG8_STAGE(PG8_SA(1, 1), a1 + hstep, voffA);
;             PG8_WAIT_V(8); PG8_WAIT_L(0); PG8_BAR; PG8_MMA(0, 0, At, B0); PG8_MMA(0, 1, At, B1); PG8_BAR; PG8_SCHED;
;             PG8_LDA(At, 0, 1); PG8_STAGE(PG8_SB(0, 0), b2, voffB); PG8_STAGE(PG8_SB(0, 1), b2 + hstep, voffB); PG8_STAGE(PG8_SA(0, 0), a2, voffA);
;             PG8_WAIT_V(8); PG8_WAIT_L(0); PG8_BAR; PG8_MMA(1, 0, At, B0); PG8_MMA(1, 1, At, B1); PG8_BAR; PG8_SCHED;
.LBB0_369:
	s_add_i32 s62, 0, 0x10000
	v_add_u32_e32 v128, s62, v142
	s_add_i32 s63, 0, 0x14000
	ds_read_b128 v[138:141], v128
	ds_read_b128 v[144:147], v128 offset:1024
	ds_read_b128 v[148:151], v128 offset:2048
	ds_read_b128 v[152:155], v128 offset:3072
	v_add_u32_e32 v128, s63, v142
	ds_read_b128 v[156:159], v128
	ds_read_b128 v[184:187], v128 offset:1024
	ds_read_b128 v[188:191], v128 offset:2048
	ds_read_b128 v[192:195], v128 offset:3072
	v_lshl_add_u64 v[130:131], s[34:35], 0, v[134:135]
	s_add_i32 m0, s44, 0xc000
	ds_read_b128 v[212:215], v143
	ds_read_b128 v[216:219], v143 offset:1024
	ds_read_b128 v[220:223], v143 offset:2048
	ds_read_b128 v[224:227], v143 offset:3072
	ds_read_b128 v[228:231], v143 offset:4096
	ds_read_b128 v[232:235], v143 offset:5120
	ds_read_b128 v[236:239], v143 offset:6144
	ds_read_b128 v[240:243], v143 offset:7168
	s_add_i32 s59, s8, 2
	s_add_u32 s60, s34, 0x80
	s_addc_u32 s9, s35, 0
	s_cmp_eq_u32 s17, s8
	s_cselect_b32 s9, s29, s9
	s_cselect_b32 s8, s28, s60
	s_cselect_b32 s61, s31, s58
	s_cselect_b32 s60, s30, s57
	global_load_lds_dwordx4 v[130:131], off
	v_lshl_add_u64 v[130:131], s[34:35], 0, v[136:137]
	s_add_i32 m0, s44, 0xe000
	s_nop 0
	global_load_lds_dwordx4 v[130:131], off
	s_waitcnt vmcnt(8)
	s_waitcnt lgkmcnt(0)
	s_barrier
	s_setprio 1
	s_waitcnt lgkmcnt(0)
	v_mfma_f32_16x16x32_bf16 v[96:99], v[138:141], v[212:215], v[96:99]
	v_mfma_f32_16x16x32_bf16 v[100:103], v[148:151], v[212:215], v[100:103]
	v_mfma_f32_16x16x32_bf16 v[104:107], v[138:141], v[220:223], v[104:107]
	v_mfma_f32_16x16x32_bf16 v[108:111], v[148:151], v[220:223], v[108:111]
	v_mfma_f32_16x16x32_bf16 v[112:115], v[138:141], v[228:231], v[112:115]
	v_mfma_f32_16x16x32_bf16 v[116:119], v[148:151], v[228:231], v[116:119]
	v_mfma_f32_16x16x32_bf16 v[120:123], v[138:141], v[236:239], v[120:123]
	v_mfma_f32_16x16x32_bf16 v[124:127], v[148:151], v[236:239], v[124:127]
	v_mfma_f32_16x16x32_bf16 v[96:99], v[144:147], v[216:219], v[96:99]
	v_mfma_f32_16x16x32_bf16 v[100:103], v[152:155], v[216:219], v[100:103]
	v_mfma_f32_16x16x32_bf16 v[104:107], v[144:147], v[224:227], v[104:107]
	v_mfma_f32_16x16x32_bf16 v[108:111], v[152:155], v[224:227], v[108:111]
	v_mfma_f32_16x16x32_bf16 v[112:115], v[144:147], v[232:235], v[112:115]
	v_mfma_f32_16x16x32_bf16 v[116:119], v[152:155], v[232:235], v[116:119]
	v_mfma_f32_16x16x32_bf16 v[120:123], v[144:147], v[240:243], v[120:123]
	v_mfma_f32_16x16x32_bf16 v[124:127], v[152:155], v[240:243], v[124:127]
	s_setprio 0
	s_setprio 1
	v_mfma_f32_16x16x32_bf16 v[32:35], v[156:159], v[212:215], v[32:35]
	v_mfma_f32_16x16x32_bf16 v[36:39], v[188:191], v[212:215], v[36:39]
	v_mfma_f32_16x16x32_bf16 v[52:55], v[156:159], v[220:223], v[52:55]
	v_mfma_f32_16x16x32_bf16 v[56:59], v[188:191], v[220:223], v[56:59]
	v_mfma_f32_16x16x32_bf16 v[72:75], v[156:159], v[228:231], v[72:75]
	v_mfma_f32_16x16x32_bf16 v[80:83], v[188:191], v[228:231], v[80:83]
	v_mfma_f32_16x16x32_bf16 v[88:91], v[156:159], v[236:239], v[88:91]
	v_mfma_f32_16x16x32_bf16 v[92:95], v[188:191], v[236:239], v[92:95]
	v_mfma_f32_16x16x32_bf16 v[32:35], v[184:187], v[216:219], v[32:35]
	v_mfma_f32_16x16x32_bf16 v[36:39], v[192:195], v[216:219], v[36:39]
	v_mfma_f32_16x16x32_bf16 v[52:55], v[184:187], v[224:227], v[52:55]
	v_mfma_f32_16x16x32_bf16 v[56:59], v[192:195], v[224:227], v[56:59]
	v_mfma_f32_16x16x32_bf16 v[72:75], v[184:187], v[232:235], v[72:75]
	v_mfma_f32_16x16x32_bf16 v[80:83], v[192:195], v[232:235], v[80:83]
	v_mfma_f32_16x16x32_bf16 v[88:91], v[184:187], v[240:243], v[88:91]
	v_mfma_f32_16x16x32_bf16 v[92:95], v[192:195], v[240:243], v[92:95]
	s_setprio 0
	s_barrier
	s_add_i32 s62, s62, s41
	v_lshl_add_u64 v[130:131], s[60:61], 0, v[178:179]
	s_mov_b32 m0, s62
	ds_read_b128 v[212:215], v143 offset:16384
	ds_read_b128 v[216:219], v143 offset:17408
	ds_read_b128 v[220:223], v143 offset:18432
	ds_read_b128 v[224:227], v143 offset:19456
	ds_read_b128 v[228:231], v143 offset:20480
	ds_read_b128 v[232:235], v143 offset:21504
	ds_read_b128 v[236:239], v143 offset:22528
	ds_read_b128 v[240:243], v143 offset:23552
	global_load_lds_dwordx4 v[130:131], off
	s_add_i32 m0, s62, 0x2000
	v_lshl_add_u64 v[160:161], s[60:61], 0, v[182:183]
	s_add_u32 s60, s60, s88
	s_addc_u32 s61, s61, 0
	s_add_i32 s62, s63, s41
	global_load_lds_dwordx4 v[160:161], off
	v_lshl_add_u64 v[244:245], s[60:61], 0, v[178:179]
	s_mov_b32 m0, s62
	v_lshl_add_u64 v[246:247], s[60:61], 0, v[182:183]
	global_load_lds_dwordx4 v[244:245], off
	s_add_i32 m0, s62, 0x2000
	v_lshl_add_u64 v[248:249], s[8:9], 0, v[176:177]
	global_load_lds_dwordx4 v[246:247], off
	s_mov_b32 m0, s44
	v_lshl_add_u64 v[250:251], s[8:9], 0, v[180:181]
	global_load_lds_dwordx4 v[248:249], off
	s_mov_b32 m0, s45
	s_nop 0
	global_load_lds_dwordx4 v[250:251], off
	s_waitcnt vmcnt(8)
	s_waitcnt lgkmcnt(0)
	s_barrier
; #define PG8_STAGE(bufoff, gbase, voff) do { _Pragma("unroll") for (int _i = 0; _i < 2; ++_i) \
;         __builtin_amdgcn_global_load_lds((const unsigned*)((const char*)(gbase) + (voff)[_i]), (PG8_LAS unsigned*)(lds + (bufoff) + ldsw + _i * 8192), 16, 0, 0); } while (0)
; #define PG8_LDA(dst, b, h) do { _Pragma("unroll") for (int m = 0; m < 4; ++m) _Pragma("unroll") for (int k = 0; k < 2; ++k) dst[m][k] = *(const PG8_LAS bf16x8*)(lds + PG8_SA(b, h) + aoff + m * 2048 + k * 1024); } while (0)
; #define PG8_LDB(dst, b, h) do { _Pragma("unroll") for (int n = 0; n < 2; ++n) _Pragma("unroll") for (int k = 0; k < 2; ++k) dst[n][k] = *(const PG8_LAS bf16x8*)(lds + PG8_SB(b, h) + boff + n * 2048 + k * 1024); } while (0)
; #define PG8_MMA(ai, bj, At, Bt) do { __builtin_amdgcn_s_setprio(1); _Pragma("unroll") for (int m = 0; m < 4; ++m) _Pragma("unroll") for (int n = 0; n < 2; ++n) _Pragma("unroll") for (int k = 0; k < 2; ++k) \
;         acc[ai][bj][m][n] = __builtin_amdgcn_mfma_f32_16x16x32_bf16(Bt[n][k], At[m][k], acc[ai][bj][m][n], 0, 0, 0); __builtin_amdgcn_s_setprio(0); } while (0)
; #define PG8_WAIT_V(n) asm volatile("s_waitcnt vmcnt(" #n ")" ::: "memory")
; #define PG8_WAIT_L(n) asm volatile("s_waitcnt lgkmcnt(" #n ")" ::: "memory")
; #define PG8_BAR __builtin_amdgcn_s_barrier()
; #define PG8_SCHED __builtin_amdgcn_sched_barrier(0)
; template <class Epi, class Sched, bool ALIGN_EPI = false, bool SP2 = false>
; __device__ __forceinline__ void gemm_phase(PG8_LAS unsigned char* lds, const Gemm g, const Sched& S, const Epi& E, const int wave_s) {
;     ...
;             PG8_WAIT_V(8); PG8_WAIT_L(0); PG8_BAR; PG8_MMA(1, 0, At, B0); PG8_MMA(1, 1, At, B1); PG8_BAR; PG8_SCHED;
;             PG8_LDB(B0, 1, 0); PG8_LDB(B1, 1, 1); PG8_SCHED; PG8_LDA(At, 1, 0); PG8_STAGE(PG8_SA(0, 1), a2 + hstep, voffA);
;             PG8_WAIT_V(8); PG8_WAIT_L(0); PG8_BAR; PG8_MMA(0, 0, At, B0); PG8_MMA(0, 1, At, B1); PG8_BAR; PG8_SCHED;
	s_setprio 1
	s_waitcnt lgkmcnt(0)
	v_mfma_f32_16x16x32_bf16 v[84:87], v[138:141], v[212:215], v[84:87]
	v_mfma_f32_16x16x32_bf16 v[76:79], v[148:151], v[212:215], v[76:79]
	v_mfma_f32_16x16x32_bf16 v[68:71], v[138:141], v[220:223], v[68:71]
	v_mfma_f32_16x16x32_bf16 v[64:67], v[148:151], v[220:223], v[64:67]
	v_mfma_f32_16x16x32_bf16 v[60:63], v[138:141], v[228:231], v[60:63]
	v_mfma_f32_16x16x32_bf16 v[48:51], v[148:151], v[228:231], v[48:51]
	v_mfma_f32_16x16x32_bf16 v[44:47], v[138:141], v[236:239], v[44:47]
	v_mfma_f32_16x16x32_bf16 v[40:43], v[148:151], v[236:239], v[40:43]
	v_mfma_f32_16x16x32_bf16 v[84:87], v[144:147], v[216:219], v[84:87]
	v_mfma_f32_16x16x32_bf16 v[76:79], v[152:155], v[216:219], v[76:79]
	v_mfma_f32_16x16x32_bf16 v[68:71], v[144:147], v[224:227], v[68:71]
	v_mfma_f32_16x16x32_bf16 v[64:67], v[152:155], v[224:227], v[64:67]
	v_mfma_f32_16x16x32_bf16 v[60:63], v[144:147], v[232:235], v[60:63]
	v_mfma_f32_16x16x32_bf16 v[48:51], v[152:155], v[232:235], v[48:51]
	v_mfma_f32_16x16x32_bf16 v[44:47], v[144:147], v[240:243], v[44:47]
	v_mfma_f32_16x16x32_bf16 v[40:43], v[152:155], v[240:243], v[40:43]
	s_setprio 0
	s_setprio 1
	v_mfma_f32_16x16x32_bf16 v[28:31], v[156:159], v[212:215], v[28:31]
	v_mfma_f32_16x16x32_bf16 v[24:27], v[188:191], v[212:215], v[24:27]
	v_mfma_f32_16x16x32_bf16 v[20:23], v[156:159], v[220:223], v[20:23]
	v_mfma_f32_16x16x32_bf16 v[16:19], v[188:191], v[220:223], v[16:19]
	v_mfma_f32_16x16x32_bf16 v[12:15], v[156:159], v[228:231], v[12:15]
	v_mfma_f32_16x16x32_bf16 v[8:11], v[188:191], v[228:231], v[8:11]
	v_mfma_f32_16x16x32_bf16 v[4:7], v[156:159], v[236:239], v[4:7]
	v_mfma_f32_16x16x32_bf16 v[0:3], v[188:191], v[236:239], v[0:3]
	v_mfma_f32_16x16x32_bf16 v[28:31], v[184:187], v[216:219], v[28:31]
	v_mfma_f32_16x16x32_bf16 v[24:27], v[192:195], v[216:219], v[24:27]
	v_mfma_f32_16x16x32_bf16 v[20:23], v[184:187], v[224:227], v[20:23]
	v_mfma_f32_16x16x32_bf16 v[16:19], v[192:195], v[224:227], v[16:19]
	v_mfma_f32_16x16x32_bf16 v[12:15], v[184:187], v[232:235], v[12:15]
	v_mfma_f32_16x16x32_bf16 v[8:11], v[192:195], v[232:235], v[8:11]
	v_mfma_f32_16x16x32_bf16 v[4:7], v[184:187], v[240:243], v[4:7]
	v_mfma_f32_16x16x32_bf16 v[0:3], v[192:195], v[240:243], v[0:3]
	s_setprio 0
	s_barrier
	s_add_i32 s60, 0, 0x18000
	v_add_u32_e32 v128, s60, v142
	s_add_i32 s61, 0, 0x1c000
	ds_read_b128 v[138:141], v128
	ds_read_b128 v[144:147], v128 offset:1024
	ds_read_b128 v[148:151], v128 offset:2048
	ds_read_b128 v[152:155], v128 offset:3072
	v_add_u32_e32 v128, s61, v142
	ds_read_b128 v[156:159], v128
	ds_read_b128 v[184:187], v128 offset:1024
	ds_read_b128 v[188:191], v128 offset:2048
	ds_read_b128 v[192:195], v128 offset:3072
	s_add_u32 s8, s8, s88
	s_addc_u32 s9, s9, 0
	s_mov_b32 m0, s46
	v_lshl_add_u64 v[206:207], s[8:9], 0, v[176:177]
	ds_read_b128 v[212:215], v143 offset:32768
	ds_read_b128 v[216:219], v143 offset:33792
	ds_read_b128 v[220:223], v143 offset:34816
	ds_read_b128 v[224:227], v143 offset:35840
	ds_read_b128 v[228:231], v143 offset:36864
	ds_read_b128 v[232:235], v143 offset:37888
	ds_read_b128 v[236:239], v143 offset:38912
	ds_read_b128 v[240:243], v143 offset:39936
	global_load_lds_dwordx4 v[206:207], off
	v_lshl_add_u64 v[206:207], s[8:9], 0, v[180:181]
	s_mov_b32 m0, s47
	s_nop 0
	global_load_lds_dwordx4 v[206:207], off
	s_waitcnt vmcnt(8)
	s_waitcnt lgkmcnt(0)
	s_barrier
	s_setprio 1
	s_waitcnt lgkmcnt(0)
	v_mfma_f32_16x16x32_bf16 v[96:99], v[138:141], v[212:215], v[96:99]
	v_mfma_f32_16x16x32_bf16 v[100:103], v[148:151], v[212:215], v[100:103]
	v_mfma_f32_16x16x32_bf16 v[104:107], v[138:141], v[220:223], v[104:107]
	v_mfma_f32_16x16x32_bf16 v[108:111], v[148:151], v[220:223], v[108:111]
	v_mfma_f32_16x16x32_bf16 v[112:115], v[138:141], v[228:231], v[112:115]
	v_mfma_f32_16x16x32_bf16 v[116:119], v[148:151], v[228:231], v[116:119]
	v_mfma_f32_16x16x32_bf16 v[120:123], v[138:141], v[236:239], v[120:123]
	v_mfma_f32_16x16x32_bf16 v[124:127], v[148:151], v[236:239], v[124:127]
	v_mfma_f32_16x16x32_bf16 v[96:99], v[144:147], v[216:219], v[96:99]
	v_mfma_f32_16x16x32_bf16 v[100:103], v[152:155], v[216:219], v[100:103]
	v_mfma_f32_16x16x32_bf16 v[104:107], v[144:147], v[224:227], v[104:107]
	v_mfma_f32_16x16x32_bf16 v[108:111], v[152:155], v[224:227], v[108:111]
	v_mfma_f32_16x16x32_bf16 v[112:115], v[144:147], v[232:235], v[112:115]
	v_mfma_f32_16x16x32_bf16 v[116:119], v[152:155], v[232:235], v[116:119]
	v_mfma_f32_16x16x32_bf16 v[120:123], v[144:147], v[240:243], v[120:123]
	v_mfma_f32_16x16x32_bf16 v[124:127], v[152:155], v[240:243], v[124:127]
	s_setprio 0
	s_setprio 1
	v_mfma_f32_16x16x32_bf16 v[32:35], v[156:159], v[212:215], v[32:35]
	v_mfma_f32_16x16x32_bf16 v[36:39], v[188:191], v[212:215], v[36:39]
	v_mfma_f32_16x16x32_bf16 v[52:55], v[156:159], v[220:223], v[52:55]
	v_mfma_f32_16x16x32_bf16 v[56:59], v[188:191], v[220:223], v[56:59]
	v_mfma_f32_16x16x32_bf16 v[72:75], v[156:159], v[228:231], v[72:75]
	v_mfma_f32_16x16x32_bf16 v[80:83], v[188:191], v[228:231], v[80:83]
	v_mfma_f32_16x16x32_bf16 v[88:91], v[156:159], v[236:239], v[88:91]
	v_mfma_f32_16x16x32_bf16 v[92:95], v[188:191], v[236:239], v[92:95]
	v_mfma_f32_16x16x32_bf16 v[32:35], v[184:187], v[216:219], v[32:35]
	v_mfma_f32_16x16x32_bf16 v[36:39], v[192:195], v[216:219], v[36:39]
	v_mfma_f32_16x16x32_bf16 v[52:55], v[184:187], v[224:227], v[52:55]
	v_mfma_f32_16x16x32_bf16 v[56:59], v[192:195], v[224:227], v[56:59]
	v_mfma_f32_16x16x32_bf16 v[72:75], v[184:187], v[232:235], v[72:75]
	v_mfma_f32_16x16x32_bf16 v[80:83], v[192:195], v[232:235], v[80:83]
	v_mfma_f32_16x16x32_bf16 v[88:91], v[184:187], v[240:243], v[88:91]
	v_mfma_f32_16x16x32_bf16 v[92:95], v[192:195], v[240:243], v[92:95]
	s_setprio 0
	s_barrier
; #define PG8_STAGE(bufoff, gbase, voff) do { _Pragma("unroll") for (int _i = 0; _i < 2; ++_i) \
;         __builtin_amdgcn_global_load_lds((const unsigned*)((const char*)(gbase) + (voff)[_i]), (PG8_LAS unsigned*)(lds + (bufoff) + ldsw + _i * 8192), 16, 0, 0); } while (0)
; #define PG8_LDA(dst, b, h) do { _Pragma("unroll") for (int m = 0; m < 4; ++m) _Pragma("unroll") for (int k = 0; k < 2; ++k) dst[m][k] = *(const PG8_LAS bf16x8*)(lds + PG8_SA(b, h) + aoff + m * 2048 + k * 1024); } while (0)
; #define PG8_MMA(ai, bj, At, Bt) do { __builtin_amdgcn_s_setprio(1); _Pragma("unroll") for (int m = 0; m < 4; ++m) _Pragma("unroll") for (int n = 0; n < 2; ++n) _Pragma("unroll") for (int k = 0; k < 2; ++k) \
;         acc[ai][bj][m][n] = __builtin_amdgcn_mfma_f32_16x16x32_bf16(Bt[n][k], At[m][k], acc[ai][bj][m][n], 0, 0, 0); __builtin_amdgcn_s_setprio(0); } while (0)
; #define PG8_WAIT_V(n) asm volatile("s_waitcnt vmcnt(" #n ")" ::: "memory")
; #define PG8_WAIT_L(n) asm volatile("s_waitcnt lgkmcnt(" #n ")" ::: "memory")
; #define PG8_BAR __builtin_amdgcn_s_barrier()
; #define PG8_SCHED __builtin_amdgcn_sched_barrier(0)
; template <class Epi, class Sched, bool ALIGN_EPI = false, bool SP2 = false>
; __device__ __forceinline__ void gemm_phase(PG8_LAS unsigned char* lds, const Gemm g, const Sched& S, const Epi& E, const int wave_s) {
;     ...
;         for (int t = 0; t < clen; t += 2) {
;     ...
;             PG8_WAIT_V(8); PG8_WAIT_L(0); PG8_BAR; PG8_MMA(0, 0, At, B0); PG8_MMA(0, 1, At, B1); PG8_BAR; PG8_SCHED;
;             PG8_LDA(At, 1, 1); PG8_STAGE(PG8_SB(1, 0), b3, voffB); PG8_STAGE(PG8_SB(1, 1), b3 + hstep, voffB); PG8_STAGE(PG8_SA(1, 0), a3, voffA);
;             PG8_WAIT_V(8); PG8_WAIT_L(0); PG8_BAR; PG8_MMA(1, 0, At, B0); PG8_MMA(1, 1, At, B1); PG8_BAR; PG8_SCHED;
	s_add_i32 s8, s60, s41
	v_lshl_add_u64 v[130:131], v[130:131], 0, s[4:5]
	s_mov_b32 m0, s8
	ds_read_b128 v[212:215], v143 offset:49152
	ds_read_b128 v[216:219], v143 offset:50176
	ds_read_b128 v[220:223], v143 offset:51200
	ds_read_b128 v[224:227], v143 offset:52224
	ds_read_b128 v[228:231], v143 offset:53248
	ds_read_b128 v[232:235], v143 offset:54272
	ds_read_b128 v[236:239], v143 offset:55296
	ds_read_b128 v[240:243], v143 offset:56320
	global_load_lds_dwordx4 v[130:131], off
	v_lshl_add_u64 v[130:131], v[160:161], 0, s[4:5]
	s_add_i32 m0, s8, 0x2000
	s_add_i32 s8, s61, s41
	global_load_lds_dwordx4 v[130:131], off
	v_lshl_add_u64 v[130:131], v[244:245], 0, s[4:5]
	s_mov_b32 m0, s8
	s_nop 0
	global_load_lds_dwordx4 v[130:131], off
	v_lshl_add_u64 v[130:131], v[246:247], 0, s[4:5]
	s_add_i32 m0, s8, 0x2000
	s_nop 0
	global_load_lds_dwordx4 v[130:131], off
	v_lshl_add_u64 v[130:131], v[248:249], 0, s[4:5]
	s_mov_b32 m0, s48
	s_nop 0
	global_load_lds_dwordx4 v[130:131], off
	v_lshl_add_u64 v[130:131], v[250:251], 0, s[4:5]
	s_mov_b32 m0, s49
	s_nop 0
	global_load_lds_dwordx4 v[130:131], off
	s_waitcnt vmcnt(8)
	s_waitcnt lgkmcnt(0)
	s_barrier
	s_setprio 1
	s_waitcnt lgkmcnt(0)
	v_mfma_f32_16x16x32_bf16 v[84:87], v[138:141], v[212:215], v[84:87]
	v_mfma_f32_16x16x32_bf16 v[76:79], v[148:151], v[212:215], v[76:79]
	v_mfma_f32_16x16x32_bf16 v[68:71], v[138:141], v[220:223], v[68:71]
	v_mfma_f32_16x16x32_bf16 v[64:67], v[148:151], v[220:223], v[64:67]
	v_mfma_f32_16x16x32_bf16 v[60:63], v[138:141], v[228:231], v[60:63]
	v_mfma_f32_16x16x32_bf16 v[48:51], v[148:151], v[228:231], v[48:51]
	v_mfma_f32_16x16x32_bf16 v[44:47], v[138:141], v[236:239], v[44:47]
	v_mfma_f32_16x16x32_bf16 v[40:43], v[148:151], v[236:239], v[40:43]
	v_mfma_f32_16x16x32_bf16 v[84:87], v[144:147], v[216:219], v[84:87]
	v_mfma_f32_16x16x32_bf16 v[76:79], v[152:155], v[216:219], v[76:79]
	v_mfma_f32_16x16x32_bf16 v[68:71], v[144:147], v[224:227], v[68:71]
	v_mfma_f32_16x16x32_bf16 v[64:67], v[152:155], v[224:227], v[64:67]
	v_mfma_f32_16x16x32_bf16 v[60:63], v[144:147], v[232:235], v[60:63]
	v_mfma_f32_16x16x32_bf16 v[48:51], v[152:155], v[232:235], v[48:51]
	v_mfma_f32_16x16x32_bf16 v[44:47], v[144:147], v[240:243], v[44:47]
	v_mfma_f32_16x16x32_bf16 v[40:43], v[152:155], v[240:243], v[40:43]
	s_setprio 0
	s_setprio 1
	v_mfma_f32_16x16x32_bf16 v[28:31], v[156:159], v[212:215], v[28:31]
	v_mfma_f32_16x16x32_bf16 v[24:27], v[188:191], v[212:215], v[24:27]
	v_mfma_f32_16x16x32_bf16 v[20:23], v[156:159], v[220:223], v[20:23]
	v_mfma_f32_16x16x32_bf16 v[16:19], v[188:191], v[220:223], v[16:19]
	v_mfma_f32_16x16x32_bf16 v[12:15], v[156:159], v[228:231], v[12:15]
	v_mfma_f32_16x16x32_bf16 v[8:11], v[188:191], v[228:231], v[8:11]
	v_mfma_f32_16x16x32_bf16 v[4:7], v[156:159], v[236:239], v[4:7]
	v_mfma_f32_16x16x32_bf16 v[0:3], v[188:191], v[236:239], v[0:3]
	v_mfma_f32_16x16x32_bf16 v[28:31], v[184:187], v[216:219], v[28:31]
	v_mfma_f32_16x16x32_bf16 v[24:27], v[192:195], v[216:219], v[24:27]
	v_mfma_f32_16x16x32_bf16 v[20:23], v[184:187], v[224:227], v[20:23]
	v_mfma_f32_16x16x32_bf16 v[16:19], v[192:195], v[224:227], v[16:19]
	v_mfma_f32_16x16x32_bf16 v[12:15], v[184:187], v[232:235], v[12:15]
	v_mfma_f32_16x16x32_bf16 v[8:11], v[192:195], v[232:235], v[8:11]
	v_mfma_f32_16x16x32_bf16 v[4:7], v[184:187], v[240:243], v[4:7]
	v_mfma_f32_16x16x32_bf16 v[0:3], v[192:195], v[240:243], v[0:3]
	s_setprio 0
	s_add_u32 s34, s34, 0x100
	s_addc_u32 s35, s35, 0
	s_add_u32 s57, s57, 0x100
	s_addc_u32 s58, s58, 0
	s_cmp_ge_i32 s59, s55
	s_mov_b32 s8, s59
	s_barrier
	s_cbranch_scc0 .LBB0_369
	s_and_b64 vcc, exec, s[26:27]
	s_cbranch_vccz .LBB0_372
	s_barrier

; #define PG8_STAGE(bufoff, gbase, voff) do { _Pragma("unroll") for (int _i = 0; _i < 2; ++_i) \
;         __builtin_amdgcn_global_load_lds((const unsigned*)((const char*)(gbase) + (voff)[_i]), (PG8_LAS unsigned*)(lds + (bufoff) + ldsw + _i * 8192), 16, 0, 0); } while (0)
; #define PG8_LDA(dst, b, h) do { _Pragma("unroll") for (int m = 0; m < 4; ++m) _Pragma("unroll") for (int k = 0; k < 2; ++k) dst[m][k] = *(const PG8_LAS bf16x8*)(lds + PG8_SA(b, h) + aoff + m * 2048 + k * 1024); } while (0)
; #define PG8_LDB(dst, b, h) do { _Pragma("unroll") for (int n = 0; n < 2; ++n) _Pragma("unroll") for (int k = 0; k < 2; ++k) dst[n][k] = *(const PG8_LAS bf16x8*)(lds + PG8_SB(b, h) + boff + n * 2048 + k * 1024); } while (0)
; #define PG8_MMA(ai, bj, At, Bt) do { __builtin_amdgcn_s_setprio(1); _Pragma("unroll") for (int m = 0; m < 4; ++m) _Pragma("unroll") for (int n = 0; n < 2; ++n) _Pragma("unroll") for (int k = 0; k < 2; ++k) \
;         acc[ai][bj][m][n] = __builtin_amdgcn_mfma_f32_16x16x32_bf16(Bt[n][k], At[m][k], acc[ai][bj][m][n], 0, 0, 0); __builtin_amdgcn_s_setprio(0); } while (0)
; #define PG8_WAIT_V(n) asm volatile("s_waitcnt vmcnt(" #n ")" ::: "memory")
; #define PG8_WAIT_L(n) asm volatile("s_waitcnt lgkmcnt(" #n ")" ::: "memory")
; #define PG8_BAR __builtin_amdgcn_s_barrier()
; #define PG8_SCHED __builtin_amdgcn_sched_barrier(0)
; template <class Epi, class Sched, bool ALIGN_EPI = false, bool SP2 = false>
; __device__ __forceinline__ void gemm_phase(PG8_LAS unsigned char* lds, const Gemm g, const Sched& S, const Epi& E, const int wave_s) {
;     ...
;             PG8_LDB(B0, 0, 0); PG8_LDB(B1, 0, 1); PG8_SCHED; PG8_LDA(At, 0, 0); PG8_STAGE(PG8_SA(1, 1), a1 + hstep, voffA);
;             PG8_WAIT_V(8); PG8_WAIT_L(0); PG8_BAR; PG8_MMA(0, 0, At, B0); PG8_MMA(0, 1, At, B1); PG8_BAR; PG8_SCHED;
;             PG8_LDA(At, 0, 1); PG8_STAGE(PG8_SB(0, 0), b2, voffB); PG8_STAGE(PG8_SB(0, 1), b2 + hstep, voffB); PG8_STAGE(PG8_SA(0, 0), a2, voffA);
;             PG8_WAIT_V(8); PG8_WAIT_L(0); PG8_BAR; PG8_MMA(1, 0, At, B0); PG8_MMA(1, 1, At, B1); PG8_BAR; PG8_SCHED;
.LBB0_523:
	s_add_i32 s51, 0, 0x10000
	v_add_u32_e32 v144, s51, v147
	s_add_i32 s54, 0, 0x14000
	ds_read_b128 v[140:143], v144
	ds_read_b128 v[150:153], v144 offset:1024
	ds_read_b128 v[154:157], v144 offset:2048
	ds_read_b128 v[158:161], v144 offset:3072
	v_add_u32_e32 v144, s54, v147
	ds_read_b128 v[174:177], v144
	ds_read_b128 v[178:181], v144 offset:1024
	ds_read_b128 v[182:185], v144 offset:2048
	ds_read_b128 v[186:189], v144 offset:3072
	v_lshl_add_u64 v[194:195], s[24:25], 0, v[136:137]
	s_add_i32 m0, s35, 0xc000
	ds_read_b128 v[190:193], v148
	ds_read_b128 v[210:213], v148 offset:1024
	ds_read_b128 v[214:217], v148 offset:2048
	ds_read_b128 v[218:221], v148 offset:3072
	ds_read_b128 v[222:225], v148 offset:4096
	ds_read_b128 v[226:229], v148 offset:5120
	ds_read_b128 v[230:233], v148 offset:6144
	ds_read_b128 v[234:237], v148 offset:7168
	s_add_u32 s2, s24, 0xfffc0080
	s_addc_u32 s3, s25, -1
	s_cmp_eq_u32 s50, 12
	s_cselect_b32 s27, s19, s3
	s_cselect_b32 s26, s46, s2
	s_cselect_b32 s3, s17, s49
	s_cselect_b32 s2, s47, s48
	global_load_lds_dwordx4 v[194:195], off
	v_lshl_add_u64 v[194:195], s[24:25], 0, v[138:139]
	s_add_i32 m0, s35, 0xe000
	s_nop 0
	global_load_lds_dwordx4 v[194:195], off
	s_waitcnt vmcnt(8)
	s_waitcnt lgkmcnt(0)
	s_barrier
	s_setprio 1
	s_waitcnt lgkmcnt(0)
	v_mfma_f32_16x16x32_bf16 v[124:127], v[140:143], v[190:193], v[124:127]
	v_mfma_f32_16x16x32_bf16 v[116:119], v[154:157], v[190:193], v[116:119]
	v_mfma_f32_16x16x32_bf16 v[108:111], v[140:143], v[214:217], v[108:111]
	v_mfma_f32_16x16x32_bf16 v[100:103], v[154:157], v[214:217], v[100:103]
	v_mfma_f32_16x16x32_bf16 v[92:95], v[140:143], v[222:225], v[92:95]
	v_mfma_f32_16x16x32_bf16 v[84:87], v[154:157], v[222:225], v[84:87]
	v_mfma_f32_16x16x32_bf16 v[76:79], v[140:143], v[230:233], v[76:79]
	v_mfma_f32_16x16x32_bf16 v[68:71], v[154:157], v[230:233], v[68:71]
	v_mfma_f32_16x16x32_bf16 v[124:127], v[150:153], v[210:213], v[124:127]
	v_mfma_f32_16x16x32_bf16 v[116:119], v[158:161], v[210:213], v[116:119]
	v_mfma_f32_16x16x32_bf16 v[108:111], v[150:153], v[218:221], v[108:111]
	v_mfma_f32_16x16x32_bf16 v[100:103], v[158:161], v[218:221], v[100:103]
	v_mfma_f32_16x16x32_bf16 v[92:95], v[150:153], v[226:229], v[92:95]
	v_mfma_f32_16x16x32_bf16 v[84:87], v[158:161], v[226:229], v[84:87]
	v_mfma_f32_16x16x32_bf16 v[76:79], v[150:153], v[234:237], v[76:79]
	v_mfma_f32_16x16x32_bf16 v[68:71], v[158:161], v[234:237], v[68:71]
	s_setprio 0
	s_setprio 1
	v_mfma_f32_16x16x32_bf16 v[120:123], v[174:177], v[190:193], v[120:123]
	v_mfma_f32_16x16x32_bf16 v[112:115], v[182:185], v[190:193], v[112:115]
	v_mfma_f32_16x16x32_bf16 v[104:107], v[174:177], v[214:217], v[104:107]
	v_mfma_f32_16x16x32_bf16 v[96:99], v[182:185], v[214:217], v[96:99]
	v_mfma_f32_16x16x32_bf16 v[88:91], v[174:177], v[222:225], v[88:91]
	v_mfma_f32_16x16x32_bf16 v[80:83], v[182:185], v[222:225], v[80:83]
	v_mfma_f32_16x16x32_bf16 v[72:75], v[174:177], v[230:233], v[72:75]
	v_mfma_f32_16x16x32_bf16 v[64:67], v[182:185], v[230:233], v[64:67]
	v_mfma_f32_16x16x32_bf16 v[120:123], v[178:181], v[210:213], v[120:123]
	v_mfma_f32_16x16x32_bf16 v[112:115], v[186:189], v[210:213], v[112:115]
	v_mfma_f32_16x16x32_bf16 v[104:107], v[178:181], v[218:221], v[104:107]
	v_mfma_f32_16x16x32_bf16 v[96:99], v[186:189], v[218:221], v[96:99]
	v_mfma_f32_16x16x32_bf16 v[88:91], v[178:181], v[226:229], v[88:91]
	v_mfma_f32_16x16x32_bf16 v[80:83], v[186:189], v[226:229], v[80:83]
	v_mfma_f32_16x16x32_bf16 v[72:75], v[178:181], v[234:237], v[72:75]
	v_mfma_f32_16x16x32_bf16 v[64:67], v[186:189], v[234:237], v[64:67]
	s_setprio 0
	s_barrier
	s_add_i32 s51, s51, s34
	v_lshl_add_u64 v[194:195], s[2:3], 0, v[128:129]
	s_mov_b32 m0, s51
	ds_read_b128 v[190:193], v148 offset:16384
	ds_read_b128 v[210:213], v148 offset:17408
	ds_read_b128 v[214:217], v148 offset:18432
	ds_read_b128 v[218:221], v148 offset:19456
	ds_read_b128 v[222:225], v148 offset:20480
	ds_read_b128 v[226:229], v148 offset:21504
	ds_read_b128 v[230:233], v148 offset:22528
	ds_read_b128 v[234:237], v148 offset:23552
	global_load_lds_dwordx4 v[194:195], off
	s_add_i32 m0, s51, 0x2000
	s_add_u32 s52, s2, 0x40000
	v_lshl_add_u64 v[238:239], s[2:3], 0, v[130:131]
	s_addc_u32 s53, s3, 0
	s_add_i32 s51, s54, s34
	global_load_lds_dwordx4 v[238:239], off
	v_lshl_add_u64 v[240:241], s[52:53], 0, v[128:129]
	s_mov_b32 m0, s51
	v_lshl_add_u64 v[242:243], s[26:27], 0, v[132:133]
	global_load_lds_dwordx4 v[240:241], off
	v_lshl_add_u64 v[240:241], s[52:53], 0, v[130:131]
	s_add_i32 m0, s51, 0x2000
	s_nop 0
	global_load_lds_dwordx4 v[240:241], off
	v_lshl_add_u64 v[240:241], s[26:27], 0, v[134:135]
	s_mov_b32 m0, s35
	s_nop 0
	global_load_lds_dwordx4 v[240:241], off
	s_mov_b32 m0, s36
	s_nop 0
	global_load_lds_dwordx4 v[242:243], off
	s_waitcnt vmcnt(8)
	s_waitcnt lgkmcnt(0)
	s_barrier
; #define PG8_STAGE(bufoff, gbase, voff) do { _Pragma("unroll") for (int _i = 0; _i < 2; ++_i) \
;         __builtin_amdgcn_global_load_lds((const unsigned*)((const char*)(gbase) + (voff)[_i]), (PG8_LAS unsigned*)(lds + (bufoff) + ldsw + _i * 8192), 16, 0, 0); } while (0)
; #define PG8_LDA(dst, b, h) do { _Pragma("unroll") for (int m = 0; m < 4; ++m) _Pragma("unroll") for (int k = 0; k < 2; ++k) dst[m][k] = *(const PG8_LAS bf16x8*)(lds + PG8_SA(b, h) + aoff + m * 2048 + k * 1024); } while (0)
; #define PG8_LDB(dst, b, h) do { _Pragma("unroll") for (int n = 0; n < 2; ++n) _Pragma("unroll") for (int k = 0; k < 2; ++k) dst[n][k] = *(const PG8_LAS bf16x8*)(lds + PG8_SB(b, h) + boff + n * 2048 + k * 1024); } while (0)
; #define PG8_MMA(ai, bj, At, Bt) do { __builtin_amdgcn_s_setprio(1); _Pragma("unroll") for (int m = 0; m < 4; ++m) _Pragma("unroll") for (int n = 0; n < 2; ++n) _Pragma("unroll") for (int k = 0; k < 2; ++k) \
;         acc[ai][bj][m][n] = __builtin_amdgcn_mfma_f32_16x16x32_bf16(Bt[n][k], At[m][k], acc[ai][bj][m][n], 0, 0, 0); __builtin_amdgcn_s_setprio(0); } while (0)
; #define PG8_WAIT_V(n) asm volatile("s_waitcnt vmcnt(" #n ")" ::: "memory")
; #define PG8_WAIT_L(n) asm volatile("s_waitcnt lgkmcnt(" #n ")" ::: "memory")
; #define PG8_BAR __builtin_amdgcn_s_barrier()
; #define PG8_SCHED __builtin_amdgcn_sched_barrier(0)
; template <class Epi, class Sched, bool ALIGN_EPI = false, bool SP2 = false>
; __device__ __forceinline__ void gemm_phase(PG8_LAS unsigned char* lds, const Gemm g, const Sched& S, const Epi& E, const int wave_s) {
;     ...
;             PG8_WAIT_V(8); PG8_WAIT_L(0); PG8_BAR; PG8_MMA(1, 0, At, B0); PG8_MMA(1, 1, At, B1); PG8_BAR; PG8_SCHED;
;             PG8_LDB(B0, 1, 0); PG8_LDB(B1, 1, 1); PG8_SCHED; PG8_LDA(At, 1, 0); PG8_STAGE(PG8_SA(0, 1), a2 + hstep, voffA);
;             PG8_WAIT_V(8); PG8_WAIT_L(0); PG8_BAR; PG8_MMA(0, 0, At, B0); PG8_MMA(0, 1, At, B1); PG8_BAR; PG8_SCHED;
	s_setprio 1
	s_waitcnt lgkmcnt(0)
	v_mfma_f32_16x16x32_bf16 v[60:63], v[140:143], v[190:193], v[60:63]
	v_mfma_f32_16x16x32_bf16 v[52:55], v[154:157], v[190:193], v[52:55]
	v_mfma_f32_16x16x32_bf16 v[44:47], v[140:143], v[214:217], v[44:47]
	v_mfma_f32_16x16x32_bf16 v[36:39], v[154:157], v[214:217], v[36:39]
	v_mfma_f32_16x16x32_bf16 v[28:31], v[140:143], v[222:225], v[28:31]
	v_mfma_f32_16x16x32_bf16 v[20:23], v[154:157], v[222:225], v[20:23]
	v_mfma_f32_16x16x32_bf16 v[12:15], v[140:143], v[230:233], v[12:15]
	v_mfma_f32_16x16x32_bf16 v[4:7], v[154:157], v[230:233], v[4:7]
	v_mfma_f32_16x16x32_bf16 v[60:63], v[150:153], v[210:213], v[60:63]
	v_mfma_f32_16x16x32_bf16 v[52:55], v[158:161], v[210:213], v[52:55]
	v_mfma_f32_16x16x32_bf16 v[44:47], v[150:153], v[218:221], v[44:47]
	v_mfma_f32_16x16x32_bf16 v[36:39], v[158:161], v[218:221], v[36:39]
	v_mfma_f32_16x16x32_bf16 v[28:31], v[150:153], v[226:229], v[28:31]
	v_mfma_f32_16x16x32_bf16 v[20:23], v[158:161], v[226:229], v[20:23]
	v_mfma_f32_16x16x32_bf16 v[12:15], v[150:153], v[234:237], v[12:15]
	v_mfma_f32_16x16x32_bf16 v[4:7], v[158:161], v[234:237], v[4:7]
	s_setprio 0
	s_setprio 1
	v_mfma_f32_16x16x32_bf16 v[56:59], v[174:177], v[190:193], v[56:59]
	v_mfma_f32_16x16x32_bf16 v[48:51], v[182:185], v[190:193], v[48:51]
	v_mfma_f32_16x16x32_bf16 v[40:43], v[174:177], v[214:217], v[40:43]
	v_mfma_f32_16x16x32_bf16 v[32:35], v[182:185], v[214:217], v[32:35]
	v_mfma_f32_16x16x32_bf16 v[24:27], v[174:177], v[222:225], v[24:27]
	v_mfma_f32_16x16x32_bf16 v[16:19], v[182:185], v[222:225], v[16:19]
	v_mfma_f32_16x16x32_bf16 v[8:11], v[174:177], v[230:233], v[8:11]
	v_mfma_f32_16x16x32_bf16 v[0:3], v[182:185], v[230:233], v[0:3]
	v_mfma_f32_16x16x32_bf16 v[56:59], v[178:181], v[210:213], v[56:59]
	v_mfma_f32_16x16x32_bf16 v[48:51], v[186:189], v[210:213], v[48:51]
	v_mfma_f32_16x16x32_bf16 v[40:43], v[178:181], v[218:221], v[40:43]
	v_mfma_f32_16x16x32_bf16 v[32:35], v[186:189], v[218:221], v[32:35]
	v_mfma_f32_16x16x32_bf16 v[24:27], v[178:181], v[226:229], v[24:27]
	v_mfma_f32_16x16x32_bf16 v[16:19], v[186:189], v[226:229], v[16:19]
	v_mfma_f32_16x16x32_bf16 v[8:11], v[178:181], v[234:237], v[8:11]
	v_mfma_f32_16x16x32_bf16 v[0:3], v[186:189], v[234:237], v[0:3]
	s_setprio 0
	s_barrier
	s_add_i32 s51, 0, 0x18000
	v_add_u32_e32 v144, s51, v147
	s_add_i32 s52, 0, 0x1c000
	ds_read_b128 v[140:143], v144
	ds_read_b128 v[150:153], v144 offset:1024
	ds_read_b128 v[154:157], v144 offset:2048
	ds_read_b128 v[158:161], v144 offset:3072
	v_add_u32_e32 v144, s52, v147
	ds_read_b128 v[174:177], v144
	ds_read_b128 v[178:181], v144 offset:1024
	ds_read_b128 v[182:185], v144 offset:2048
	ds_read_b128 v[186:189], v144 offset:3072
	s_add_u32 s26, s26, 0x40000
	s_addc_u32 s27, s27, 0
	s_mov_b32 m0, s37
	v_lshl_add_u64 v[244:245], s[26:27], 0, v[134:135]
	ds_read_b128 v[190:193], v148 offset:32768
	ds_read_b128 v[210:213], v148 offset:33792
	ds_read_b128 v[214:217], v148 offset:34816
	ds_read_b128 v[218:221], v148 offset:35840
	ds_read_b128 v[222:225], v148 offset:36864
	ds_read_b128 v[226:229], v148 offset:37888
	ds_read_b128 v[230:233], v148 offset:38912
	ds_read_b128 v[234:237], v148 offset:39936
	global_load_lds_dwordx4 v[244:245], off
	v_lshl_add_u64 v[244:245], s[26:27], 0, v[132:133]
	s_mov_b32 m0, s38
	s_nop 0
	global_load_lds_dwordx4 v[244:245], off
	s_waitcnt vmcnt(8)
	s_waitcnt lgkmcnt(0)
	s_barrier
	s_setprio 1
	s_waitcnt lgkmcnt(0)
	v_mfma_f32_16x16x32_bf16 v[124:127], v[140:143], v[190:193], v[124:127]
	v_mfma_f32_16x16x32_bf16 v[116:119], v[154:157], v[190:193], v[116:119]
	v_mfma_f32_16x16x32_bf16 v[108:111], v[140:143], v[214:217], v[108:111]
	v_mfma_f32_16x16x32_bf16 v[100:103], v[154:157], v[214:217], v[100:103]
	v_mfma_f32_16x16x32_bf16 v[92:95], v[140:143], v[222:225], v[92:95]
	v_mfma_f32_16x16x32_bf16 v[84:87], v[154:157], v[222:225], v[84:87]
	v_mfma_f32_16x16x32_bf16 v[76:79], v[140:143], v[230:233], v[76:79]
	v_mfma_f32_16x16x32_bf16 v[68:71], v[154:157], v[230:233], v[68:71]
	v_mfma_f32_16x16x32_bf16 v[124:127], v[150:153], v[210:213], v[124:127]
	v_mfma_f32_16x16x32_bf16 v[116:119], v[158:161], v[210:213], v[116:119]
	v_mfma_f32_16x16x32_bf16 v[108:111], v[150:153], v[218:221], v[108:111]
	v_mfma_f32_16x16x32_bf16 v[100:103], v[158:161], v[218:221], v[100:103]
	v_mfma_f32_16x16x32_bf16 v[92:95], v[150:153], v[226:229], v[92:95]
	v_mfma_f32_16x16x32_bf16 v[84:87], v[158:161], v[226:229], v[84:87]
	v_mfma_f32_16x16x32_bf16 v[76:79], v[150:153], v[234:237], v[76:79]
	v_mfma_f32_16x16x32_bf16 v[68:71], v[158:161], v[234:237], v[68:71]
	s_setprio 0
	s_setprio 1
	v_mfma_f32_16x16x32_bf16 v[120:123], v[174:177], v[190:193], v[120:123]
	v_mfma_f32_16x16x32_bf16 v[112:115], v[182:185], v[190:193], v[112:115]
	v_mfma_f32_16x16x32_bf16 v[104:107], v[174:177], v[214:217], v[104:107]
	v_mfma_f32_16x16x32_bf16 v[96:99], v[182:185], v[214:217], v[96:99]
	v_mfma_f32_16x16x32_bf16 v[88:91], v[174:177], v[222:225], v[88:91]
	v_mfma_f32_16x16x32_bf16 v[80:83], v[182:185], v[222:225], v[80:83]
	v_mfma_f32_16x16x32_bf16 v[72:75], v[174:177], v[230:233], v[72:75]
	v_mfma_f32_16x16x32_bf16 v[64:67], v[182:185], v[230:233], v[64:67]
	v_mfma_f32_16x16x32_bf16 v[120:123], v[178:181], v[210:213], v[120:123]
	v_mfma_f32_16x16x32_bf16 v[112:115], v[186:189], v[210:213], v[112:115]
	v_mfma_f32_16x16x32_bf16 v[104:107], v[178:181], v[218:221], v[104:107]
	v_mfma_f32_16x16x32_bf16 v[96:99], v[186:189], v[218:221], v[96:99]
	v_mfma_f32_16x16x32_bf16 v[88:91], v[178:181], v[226:229], v[88:91]
	v_mfma_f32_16x16x32_bf16 v[80:83], v[186:189], v[226:229], v[80:83]
	v_mfma_f32_16x16x32_bf16 v[72:75], v[178:181], v[234:237], v[72:75]
	v_mfma_f32_16x16x32_bf16 v[64:67], v[186:189], v[234:237], v[64:67]
	s_setprio 0
	s_barrier
; #define PG8_STAGE(bufoff, gbase, voff) do { _Pragma("unroll") for (int _i = 0; _i < 2; ++_i) \
;         __builtin_amdgcn_global_load_lds((const unsigned*)((const char*)(gbase) + (voff)[_i]), (PG8_LAS unsigned*)(lds + (bufoff) + ldsw + _i * 8192), 16, 0, 0); } while (0)
; #define PG8_LDA(dst, b, h) do { _Pragma("unroll") for (int m = 0; m < 4; ++m) _Pragma("unroll") for (int k = 0; k < 2; ++k) dst[m][k] = *(const PG8_LAS bf16x8*)(lds + PG8_SA(b, h) + aoff + m * 2048 + k * 1024); } while (0)
; #define PG8_MMA(ai, bj, At, Bt) do { __builtin_amdgcn_s_setprio(1); _Pragma("unroll") for (int m = 0; m < 4; ++m) _Pragma("unroll") for (int n = 0; n < 2; ++n) _Pragma("unroll") for (int k = 0; k < 2; ++k) \
;         acc[ai][bj][m][n] = __builtin_amdgcn_mfma_f32_16x16x32_bf16(Bt[n][k], At[m][k], acc[ai][bj][m][n], 0, 0, 0); __builtin_amdgcn_s_setprio(0); } while (0)
; #define PG8_WAIT_V(n) asm volatile("s_waitcnt vmcnt(" #n ")" ::: "memory")
; #define PG8_WAIT_L(n) asm volatile("s_waitcnt lgkmcnt(" #n ")" ::: "memory")
; #define PG8_BAR __builtin_amdgcn_s_barrier()
; #define PG8_SCHED __builtin_amdgcn_sched_barrier(0)
; template <class Epi, class Sched, bool ALIGN_EPI = false, bool SP2 = false>
; __device__ __forceinline__ void gemm_phase(PG8_LAS unsigned char* lds, const Gemm g, const Sched& S, const Epi& E, const int wave_s) {
;     ...
;         for (int t = 0; t < clen; t += 2) {
;     ...
;             PG8_WAIT_V(8); PG8_WAIT_L(0); PG8_BAR; PG8_MMA(0, 0, At, B0); PG8_MMA(0, 1, At, B1); PG8_BAR; PG8_SCHED;
;             PG8_LDA(At, 1, 1); PG8_STAGE(PG8_SB(1, 0), b3, voffB); PG8_STAGE(PG8_SB(1, 1), b3 + hstep, voffB); PG8_STAGE(PG8_SA(1, 0), a3, voffA);
;             PG8_WAIT_V(8); PG8_WAIT_L(0); PG8_BAR; PG8_MMA(1, 0, At, B0); PG8_MMA(1, 1, At, B1); PG8_BAR; PG8_SCHED;
	s_add_i32 s26, s51, s34
	v_lshl_add_u64 v[194:195], v[194:195], 0, s[4:5]
	s_mov_b32 m0, s26
	ds_read_b128 v[190:193], v148 offset:49152
	ds_read_b128 v[210:213], v148 offset:50176
	ds_read_b128 v[214:217], v148 offset:51200
	ds_read_b128 v[218:221], v148 offset:52224
	ds_read_b128 v[222:225], v148 offset:53248
	ds_read_b128 v[226:229], v148 offset:54272
	ds_read_b128 v[230:233], v148 offset:55296
	ds_read_b128 v[234:237], v148 offset:56320
	global_load_lds_dwordx4 v[194:195], off
	s_add_i32 m0, s26, 0x2000
	s_add_u32 s2, s2, 0x40080
	v_lshl_add_u64 v[194:195], v[238:239], 0, s[4:5]
	s_addc_u32 s3, s3, 0
	s_add_i32 s26, s52, s34
	global_load_lds_dwordx4 v[194:195], off
	v_lshl_add_u64 v[194:195], s[2:3], 0, v[128:129]
	s_mov_b32 m0, s26
	s_nop 0
	global_load_lds_dwordx4 v[194:195], off
	v_lshl_add_u64 v[194:195], s[2:3], 0, v[130:131]
	s_add_i32 m0, s26, 0x2000
	s_nop 0
	global_load_lds_dwordx4 v[194:195], off
	v_lshl_add_u64 v[194:195], v[240:241], 0, s[4:5]
	s_mov_b32 m0, s41
	s_nop 0
	global_load_lds_dwordx4 v[194:195], off
	v_lshl_add_u64 v[194:195], v[242:243], 0, s[4:5]
	s_mov_b32 m0, s42
	s_nop 0
	global_load_lds_dwordx4 v[194:195], off
	s_waitcnt vmcnt(8)
	s_waitcnt lgkmcnt(0)
	s_barrier
	s_setprio 1
	s_waitcnt lgkmcnt(0)
	v_mfma_f32_16x16x32_bf16 v[60:63], v[140:143], v[190:193], v[60:63]
	v_mfma_f32_16x16x32_bf16 v[52:55], v[154:157], v[190:193], v[52:55]
	v_mfma_f32_16x16x32_bf16 v[44:47], v[140:143], v[214:217], v[44:47]
	v_mfma_f32_16x16x32_bf16 v[36:39], v[154:157], v[214:217], v[36:39]
	v_mfma_f32_16x16x32_bf16 v[28:31], v[140:143], v[222:225], v[28:31]
	v_mfma_f32_16x16x32_bf16 v[20:23], v[154:157], v[222:225], v[20:23]
	v_mfma_f32_16x16x32_bf16 v[12:15], v[140:143], v[230:233], v[12:15]
	v_mfma_f32_16x16x32_bf16 v[4:7], v[154:157], v[230:233], v[4:7]
	v_mfma_f32_16x16x32_bf16 v[60:63], v[150:153], v[210:213], v[60:63]
	v_mfma_f32_16x16x32_bf16 v[52:55], v[158:161], v[210:213], v[52:55]
	v_mfma_f32_16x16x32_bf16 v[44:47], v[150:153], v[218:221], v[44:47]
	v_mfma_f32_16x16x32_bf16 v[36:39], v[158:161], v[218:221], v[36:39]
	v_mfma_f32_16x16x32_bf16 v[28:31], v[150:153], v[226:229], v[28:31]
	v_mfma_f32_16x16x32_bf16 v[20:23], v[158:161], v[226:229], v[20:23]
	v_mfma_f32_16x16x32_bf16 v[12:15], v[150:153], v[234:237], v[12:15]
	v_mfma_f32_16x16x32_bf16 v[4:7], v[158:161], v[234:237], v[4:7]
	s_setprio 0
	s_setprio 1
	v_mfma_f32_16x16x32_bf16 v[56:59], v[174:177], v[190:193], v[56:59]
	v_mfma_f32_16x16x32_bf16 v[48:51], v[182:185], v[190:193], v[48:51]
	v_mfma_f32_16x16x32_bf16 v[40:43], v[174:177], v[214:217], v[40:43]
	v_mfma_f32_16x16x32_bf16 v[32:35], v[182:185], v[214:217], v[32:35]
	v_mfma_f32_16x16x32_bf16 v[24:27], v[174:177], v[222:225], v[24:27]
	v_mfma_f32_16x16x32_bf16 v[16:19], v[182:185], v[222:225], v[16:19]
	v_mfma_f32_16x16x32_bf16 v[8:11], v[174:177], v[230:233], v[8:11]
	v_mfma_f32_16x16x32_bf16 v[0:3], v[182:185], v[230:233], v[0:3]
	v_mfma_f32_16x16x32_bf16 v[56:59], v[178:181], v[210:213], v[56:59]
	v_mfma_f32_16x16x32_bf16 v[48:51], v[186:189], v[210:213], v[48:51]
	v_mfma_f32_16x16x32_bf16 v[40:43], v[178:181], v[218:221], v[40:43]
	v_mfma_f32_16x16x32_bf16 v[32:35], v[186:189], v[218:221], v[32:35]
	v_mfma_f32_16x16x32_bf16 v[24:27], v[178:181], v[226:229], v[24:27]
	v_mfma_f32_16x16x32_bf16 v[16:19], v[186:189], v[226:229], v[16:19]
	v_mfma_f32_16x16x32_bf16 v[8:11], v[178:181], v[234:237], v[8:11]
	v_mfma_f32_16x16x32_bf16 v[0:3], v[186:189], v[234:237], v[0:3]
	s_setprio 0
	s_add_i32 s50, s50, 2
	s_add_u32 s24, s24, 0x100
	s_addc_u32 s25, s25, 0
	s_add_u32 s48, s48, 0x100
	s_addc_u32 s49, s49, 0
	s_cmp_gt_u32 s50, 13
	s_barrier
	s_cbranch_scc0 .LBB0_523
	s_and_b64 vcc, exec, s[14:15]
	s_cbranch_vccz .LBB0_526
	s_barrier
